# PH2: KVUP mini tasks and x0 tasks assigned to workgroups bx 128..199 (no SLOC unit) instead of vcu order
# speedup vs baseline: 1.0008x; 1.0008x over previous
; #define LAS __attribute__((address_space(3)))
; template <int KIND>
; __device__ __forceinline__ void mini_task(const Ptrs& P, const bf16* A, int lda, const bf16* B, int ldb, int K, int row0, int cb, LAS unsigned char* lds) {
;     const int tid = threadIdx.x, wave = __builtin_amdgcn_readfirstlane(tid >> 6), lane = tid & 63, r32 = lane & 31, hi = lane >> 5;
;     const int kw = K >> 3;
;     const bf16* ap = A + (size_t)r32 * lda + wave * kw + hi * 8; const bf16* bp = B + (size_t)r32 * ldb + wave * kw + hi * 8;
;     const int erow = row0 + (tid >> 4); const bool emeta = row0 >= MTOK;
;     float e_rs = 0.f; f32x4 e_cs0 = {}, e_cs1 = {};
;     if constexpr (KIND == MK_KVUP) e_rs = P.ssq_kv_()[erow]; else e_rs = P.rs1_()[erow];
;     if constexpr (KIND == MK_KR) { const int epos = emeta ? ((tid >> 4) < NMETA ? (tid >> 4) : 0) : NMETA + (erow & 4095); const int ejp = (tid & 15) >> 1;
; __global__ void __launch_bounds__(NWAVES * 64, 2) hybrid_fwd(Args args) {
;     ...
;     if (IN(2)) for (int rep2_ = 0; rep2_ < 1 + PROBE_CNT(2); ++rep2_) {
;         __syncthreads();
;         for (int tk = vcu; tk < 64; tk += G) mini_task<MK_KVUP>(P, P.kvlat_() + (size_t)MTOK * 512, 512, P.wkv_() + (size_t)tk * 64 * 512, 512, 512, MTOK, tk, lds);
;         for (int pc = 0; pc < 8; ++pc) if ((64 + pc) % G == vcu) { const int e = pc * 512 + tid, g = e >> 6, n = e & 63; float xr = 0.f, xi = 0.f;
.LBB0_405:
	s_cmp_lt_i32 s90, 3
	s_cselect_b64 s[4:5], -1, 0
	s_and_b64 s[18:19], s[4:5], s[0:1]
	v_writelane_b32 v244, s84, 25
	s_andn2_b64 vcc, exec, s[18:19]
	s_nop 0
	v_writelane_b32 v244, s85, 26
	s_cbranch_vccnz .LBB0_539
	v_and_b32_e32 v151, 15, v0
	s_sub_i32 s98, s2, 0x80
	s_cmp_gt_u32 s98, 63
	v_lshrrev_b32_e32 v64, 5, v0
	v_lshrrev_b32_e32 v34, 4, v0
	v_lshlrev_b32_e32 v35, 2, v151
	s_barrier
	s_cbranch_scc1 .LBB0_411
	v_and_b32_e32 v6, 31, v0
	v_and_b32_e32 v7, 1, v64
	v_lshlrev_b32_e32 v36, 10, v6
	v_mov_b32_e32 v37, 0
	v_lshl_add_u64 v[2:3], s[86:87], 0, v[36:37]
	v_lshlrev_b32_e32 v4, 4, v7
	v_mov_b32_e32 v5, v37
	v_lshl_add_u64 v[2:3], v[2:3], 0, v[4:5]
	s_mov_b64 s[0:1], 0x8e00000
	v_lshl_add_u64 v[38:39], v[2:3], 0, s[0:1]
	v_lshlrev_b32_e32 v2, 2, v34
	v_mov_b32_e32 v3, v37
	v_lshl_add_u64 v[2:3], s[86:87], 0, v[2:3]
	s_mov_b64 s[0:1], 0x28000
	v_lshl_add_u64 v[40:41], v[2:3], 0, s[0:1]
	v_lshlrev_b32_e32 v2, 10, v7
	v_lshlrev_b32_e32 v3, 2, v6
	v_add3_u32 v44, 0, v2, v3
	s_ashr_i32 s97, s96, 31
	v_lshrrev_b32_e32 v2, 1, v0
	s_mov_b32 s99, 0
	s_lshl_b64 s[4:5], s[98:99], 16
	v_and_b32_e32 v2, 16, v2
	v_or3_b32 v2, s4, v36, v2
	v_mov_b32_e32 v3, s5
	s_movk_i32 s0, 0x100
	v_lshl_add_u32 v4, v34, 8, 0
	v_lshlrev_b32_e32 v5, 4, v151
	v_lshl_add_u64 v[2:3], s[86:87], 0, v[2:3]
	s_mov_b64 s[4:5], 0x2000000
	s_ashr_i32 s93, s92, 31
	v_cmp_gt_u32_e64 s[0:1], s0, v0
	v_lshl_add_u64 v[42:43], v[2:3], 0, s[4:5]
	s_lshl_b64 s[6:7], s[92:93], 16
	s_lshl_b32 s3, s98, 6
	s_lshl_b32 s4, s92, 6
	v_add_u32_e32 v45, v4, v5
	v_mov_b32_e32 v46, 0x358637bd
	s_mov_b32 s5, 0x800000
	s_mov_b32 s10, 0xc100000
	s_mov_b32 s11, s98
	s_branch .LBB0_409

; __global__ void __launch_bounds__(NWAVES * 64, 2) hybrid_fwd(Args args) {
;     ...
;         for (int pc = 0; pc < 8; ++pc) if ((64 + pc) % G == vcu) { const int e = pc * 512 + tid, g = e >> 6, n = e & 63; float xr = 0.f, xi = 0.f;
;             for (int s = 0; s < NMETA; ++s) { const f32x2 a = P.apow_()[((size_t)g * 17 + (15 - s)) * 64 + n]; float br = 0.f, bi = 0.f;
;                 for (int q = 0; q < 16; ++q) { const f32x2 w = P.bbar_()[((size_t)g * 64 + n) * 16 + q]; const float uu = P.umeta_()[s * 1024 + g * 16 + q]; br += w.x * uu; bi += w.y * uu; }
;                 xr += a.x * br - a.y * bi; xi += a.x * bi + a.y * br; }
;             P.x0_()[e] = (f32x2){xr, xi}; }
.LBB0_413:
	s_or_b32 s16, s4, 64
	s_mul_hi_u32 s17, s16, s5
	s_mul_i32 s17, s17, s3
	s_sub_i32 s16, s16, s17
	s_sub_i32 s17, s16, s3
	s_cmp_ge_u32 s16, s3
	s_cselect_b32 s16, s17, s16
	s_sub_i32 s17, s16, s3
	s_cmp_ge_u32 s16, s3
	s_cselect_b32 s16, s17, s16
	s_cmp_lg_u32 s16, s98
	s_cbranch_scc1 .LBB0_412
	v_lshl_or_b32 v44, s4, 9, v0
	v_lshrrev_b32_e32 v36, 6, v44
	v_lshlrev_b64 v[2:3], 13, v[36:37]
	v_lshl_add_u64 v[30:31], v[38:39], 0, v[2:3]
	global_load_dwordx4 v[2:5], v[30:31], off offset:112
	global_load_dwordx4 v[6:9], v[30:31], off offset:96
	global_load_dwordx4 v[10:13], v[30:31], off offset:80
	global_load_dwordx4 v[14:17], v[30:31], off offset:64
	global_load_dwordx4 v[18:21], v[30:31], off offset:48
	global_load_dwordx4 v[22:25], v[30:31], off offset:32
	global_load_dwordx4 v[26:29], v[30:31], off
	s_nop 0
	global_load_dwordx4 v[30:33], v[30:31], off offset:16
	v_mov_b32_e32 v46, 0
	s_mov_b32 s16, 16
	v_mov_b64_e32 v[48:49], v[40:41]
	v_mov_b64_e32 v[50:51], v[42:43]
	v_mov_b32_e32 v47, v46
	s_waitcnt vmcnt(7)
	v_mov_b32_e32 v52, v2
	v_mov_b32_e32 v53, v4
	s_waitcnt vmcnt(6)
	v_mov_b32_e32 v54, v6
	v_mov_b32_e32 v55, v8
	s_waitcnt vmcnt(5)
	v_mov_b32_e32 v56, v10
	v_mov_b32_e32 v57, v12
	s_waitcnt vmcnt(4)
	v_mov_b32_e32 v58, v14
	v_mov_b32_e32 v59, v16
	s_waitcnt vmcnt(3)
	v_mov_b32_e32 v60, v18
	v_mov_b32_e32 v61, v20
	s_waitcnt vmcnt(2)
	v_mov_b32_e32 v62, v22
	v_mov_b32_e32 v63, v24
	v_mov_b32_e32 v4, v3
	v_mov_b32_e32 v8, v7
	v_mov_b32_e32 v12, v11
	v_mov_b32_e32 v16, v15
	v_mov_b32_e32 v20, v19
	v_mov_b32_e32 v24, v23
